# NA unit prologue de-serialised: rpb load issued with q and tile-0 loads, one barrier removed, LDS writes moved after the mask setup
# speedup vs baseline: 1.0099x; 1.0001x over previous
.LBB0_703:
	s_and_b32 s13, s0, 15
	s_and_b32 s0, s1, 15
	s_lshl_b32 s1, s0, 2
	v_sub_u32_e64 v0, s1, 1 clamp
	s_max_u32 s14, s1, 4
	v_readfirstlane_b32 s3, v0
	s_min_u32 s15, s3, 56
	v_mov_b32_e32 v0, v128
	s_movk_i32 s3, 0x1d1
	s_barrier
	s_nop 0
	v_min_u32_e32 v156, 0x1d0, v128
	v_lshlrev_b32_e32 v156, 2, v156
	v_readlane_b32 s98, v252, 56
	v_readlane_b32 s99, v252, 57
	s_mul_i32 s32, s13, 0x744
	s_add_u32 s98, s98, s32
	s_addc_u32 s99, s99, 0
	global_load_dword v157, v156, s[98:99]
.LBB0_711:
	s_lshl_b32 s4, s12, 12
	s_addk_i32 s4, 0x2000
	s_lshl_b32 s5, s0, 8
	s_sub_i32 s39, s15, s14
	s_or_b32 s5, s4, s5
	s_add_i32 s3, s14, -4
	s_add_i32 s33, s39, 12
	s_mul_hi_i32 s6, s5, 0x1800
	s_mulk_i32 s5, 0x1800
	v_readlane_b32 s16, v254, 62
	v_readlane_b32 s17, v254, 63
	s_add_u32 s5, s16, s5
	s_addc_u32 s6, s17, s6
	s_lshl_b32 s8, s13, 6
	s_lshl_b32 s18, s13, 7
	s_add_u32 s10, s5, s18
	s_addc_u32 s11, s6, 0
	s_lshl_b32 s5, s3, 6
	s_add_i32 s5, s5, s4
	s_mul_hi_i32 s6, s5, 0x1800
	s_mulk_i32 s5, 0x1800
	s_add_u32 s5, s16, s5
	s_addc_u32 s6, s17, s6
	s_add_u32 s40, s5, s18
	s_addc_u32 s41, s6, 0
	s_mul_i32 s13, s13, 0x500000
	v_readlane_b32 s6, v255, 0
	v_readlane_b32 s7, v255, 1
	s_add_u32 s6, s6, s13
	s_addc_u32 s7, s7, 0
	s_ashr_i32 s5, s4, 31
	s_lshl_b64 s[4:5], s[4:5], 1
	s_add_u32 s4, s6, s4
	s_addc_u32 s5, s7, s5
	s_lshl_b32 s6, s3, 7
	s_add_u32 s28, s4, s6
	s_addc_u32 s29, s5, 0
	s_lshl_b32 s4, s12, 8
	s_ashr_i32 s5, s4, 31
	s_lshl_b64 s[16:17], s[4:5], 11
	s_lshl_b32 s4, s12, 10
	s_or_b32 s4, s4, s8
	s_ashr_i32 s5, s4, 31
	s_lshl_b64 s[4:5], s[4:5], 9
	v_readlane_b32 s6, v255, 2
	v_mov_b32_e32 v4, v128
	v_readlane_b32 s7, v255, 3
	s_add_u32 s36, s6, s4
	s_addc_u32 s37, s7, s5
	v_readfirstlane_b32 s6, v4
	s_ashr_i32 s7, s6, 1
	v_mov_b32_e32 v0, s7
	s_movk_i32 s4, 0xffe0
	v_bfe_u32 v5, v4, 5, 1
	v_bfi_b32 v2, s4, v0, v4
	v_mov_b64_e32 v[0:1], s[10:11]
	s_movk_i32 s4, 0x1800
	v_mad_i64_i32 v[88:89], s[4:5], v2, s4, v[0:1]
	v_lshlrev_b32_e32 v90, 4, v5
	v_mov_b32_e32 v91, v131
	v_lshl_add_u64 v[0:1], v[88:89], 0, v[90:91]
	global_load_dwordx4 v[64:67], v[0:1], off
	global_load_dwordx4 v[68:71], v[0:1], off offset:32
	global_load_dwordx4 v[72:75], v[0:1], off offset:64
	global_load_dwordx4 v[76:79], v[0:1], off offset:96
	v_lshlrev_b32_e32 v6, 3, v4
	v_ashrrev_i32_e32 v92, 3, v4
	v_and_b32_e32 v16, 56, v6
	s_mov_b64 s[4:5], -1
	s_cmp_lt_i32 s39, -11
	v_lshlrev_b32_e32 v130, 1, v16
	v_ashrrev_i32_e32 v93, 31, v92
	s_cbranch_scc0 .LBB0_713
	s_add_u32 s4, s56, s16
	s_addc_u32 s5, s57, s17
	s_lshl_b32 s8, s8, 1
	s_add_u32 s4, s4, s8
	s_addc_u32 s5, s5, 0
	s_lshl_b32 s8, s33, 6
	v_subrev_u32_e32 v0, s8, v92
	v_ashrrev_i32_e32 v1, 31, v0
	v_lshlrev_b64 v[2:3], 9, v[92:93]
	s_sub_i32 s26, 0, s8
	v_lshlrev_b64 v[0:1], 11, v[0:1]
	v_lshl_add_u64 v[2:3], s[36:37], 0, v[2:3]
	v_lshl_add_u64 v[0:1], s[4:5], 0, v[0:1]
	v_lshl_add_u64 v[2:3], s[26:27], 1, v[2:3]
	v_lshl_add_u64 v[0:1], v[0:1], 0, v[130:131]
	v_lshl_add_u64 v[2:3], v[2:3], 0, v[130:131]
	s_mov_b64 s[4:5], 0

.LBB0_715:
	global_load_dwordx4 v[80:83], v[0:1], off
	global_load_dwordx4 v[84:87], v[2:3], off
	s_movk_i32 s4, 0x48
	v_mul_lo_u32 v7, v92, s4
	v_and_b32_e32 v6, 48, v6
	v_add_lshl_u32 v91, v7, v16, 1
	v_add_u32_e32 v6, v7, v6
	v_lshlrev_b32_e32 v7, 2, v4
	v_and_or_b32 v6, v7, 4, v6
	v_lshlrev_b32_e32 v93, 1, v6
	v_add_u32_e32 v0, 0, v91
	s_mov_b64 s[4:5], -1
	s_cmp_gt_i32 s39, -16
	v_lshlrev_b32_e32 v97, 2, v5
	s_cbranch_scc1 .LBB0_717
	v_lshlrev_b32_e32 v130, 2, v5
	s_mov_b64 s[4:5], 0
.LBB0_717:
	s_andn2_b64 vcc, exec, s[4:5]
	s_cbranch_vccnz .LBB0_799
	v_and_b32_e32 v0, 31, v4
	v_and_or_b32 v2, s7, 32, v0
	v_sub_u32_e64 v3, v2, 8 clamp
	v_min_u32_e32 v3, 48, v3
	v_mul_u32_u24_e32 v4, 0x48, v0
	v_mul_u32_u24_e32 v98, 0x90, v0
	v_or_b32_e32 v0, 32, v97
	v_lshlrev_b32_e32 v1, 3, v5
	v_sub_u32_e32 v0, v0, v3
	v_add_lshl_u32 v99, v1, v4, 1
	v_sub_u32_e32 v1, v97, v3
	v_cmp_gt_u32_e64 s[44:45], 16, v0
	v_or_b32_e32 v0, 1, v97
	v_cmp_gt_u32_e64 s[42:43], 16, v1
	v_or_b32_e32 v1, 33, v97
	v_sub_u32_e32 v0, v0, v3
	v_cmp_gt_u32_e64 s[46:47], 16, v0
	v_sub_u32_e32 v0, v1, v3
	v_cmp_gt_u32_e64 s[48:49], 16, v0
	v_or_b32_e32 v0, 2, v97
	v_or_b32_e32 v1, 34, v97
	v_sub_u32_e32 v0, v0, v3
	v_cmp_gt_u32_e64 s[50:51], 16, v0
	v_sub_u32_e32 v0, v1, v3
	v_cmp_gt_u32_e64 s[52:53], 16, v0
	v_or_b32_e32 v0, 3, v97
	v_or_b32_e32 v1, 35, v97
	v_sub_u32_e32 v0, v0, v3
	v_cmp_gt_u32_e64 s[54:55], 16, v0
	v_sub_u32_e32 v0, v1, v3
	s_mov_b64 s[24:25], s[56:57]
	v_cmp_gt_u32_e64 s[56:57], 16, v0
	v_or_b32_e32 v0, 8, v97
	v_or_b32_e32 v1, 40, v97
	v_sub_u32_e32 v0, v0, v3
	v_cmp_gt_u32_e64 s[58:59], 16, v0
	v_sub_u32_e32 v0, v1, v3
	v_cmp_gt_u32_e64 s[60:61], 16, v0
	v_or_b32_e32 v0, 9, v97
	v_or_b32_e32 v1, 41, v97
	v_sub_u32_e32 v0, v0, v3
	v_cmp_gt_u32_e64 s[62:63], 16, v0
	v_sub_u32_e32 v0, v1, v3
	v_cmp_gt_u32_e64 s[64:65], 16, v0
	v_or_b32_e32 v0, 10, v97
	v_or_b32_e32 v1, 42, v97
	v_sub_u32_e32 v0, v0, v3
	v_cmp_gt_u32_e64 s[66:67], 16, v0
	v_sub_u32_e32 v0, v1, v3
	v_cmp_gt_u32_e64 s[68:69], 16, v0
	v_or_b32_e32 v0, 11, v97
	v_or_b32_e32 v1, 43, v97
	v_sub_u32_e32 v0, v0, v3
	v_cmp_gt_u32_e64 s[70:71], 16, v0
	v_sub_u32_e32 v0, v1, v3
	v_cmp_gt_u32_e64 s[72:73], 16, v0
	v_or_b32_e32 v0, 16, v97
	v_or_b32_e32 v1, 48, v97
	v_sub_u32_e32 v0, v0, v3
	v_cmp_gt_u32_e64 s[74:75], 16, v0
	v_sub_u32_e32 v0, v1, v3
	v_cmp_gt_u32_e64 s[76:77], 16, v0
	v_or_b32_e32 v0, 17, v97
	v_or_b32_e32 v1, 49, v97
	v_sub_u32_e32 v0, v0, v3
	v_cmp_gt_u32_e64 s[78:79], 16, v0
	v_sub_u32_e32 v0, v1, v3
	v_cmp_gt_u32_e64 s[80:81], 16, v0
	v_or_b32_e32 v0, 18, v97
	v_or_b32_e32 v1, 50, v97
	v_sub_u32_e32 v0, v0, v3
	v_cmp_gt_u32_e64 s[82:83], 16, v0
	v_sub_u32_e32 v0, v1, v3
	v_cmp_gt_u32_e64 s[84:85], 16, v0
	v_or_b32_e32 v0, 19, v97
	v_or_b32_e32 v1, 51, v97
	v_sub_u32_e32 v0, v0, v3
	v_cmp_gt_u32_e64 s[86:87], 16, v0
	v_sub_u32_e32 v0, v1, v3
	v_cmp_gt_u32_e64 s[88:89], 16, v0
	v_or_b32_e32 v0, 24, v97
	v_or_b32_e32 v1, 56, v97
	v_sub_u32_e32 v0, v0, v3
	v_cmp_gt_u32_e64 s[90:91], 16, v0
	v_sub_u32_e32 v0, v1, v3
	v_cmp_gt_u32_e64 s[92:93], 16, v0
	v_or_b32_e32 v0, 25, v97
	s_ashr_i32 s19, s6, 7
	v_or_b32_e32 v1, 57, v97
	v_sub_u32_e32 v0, v0, v3
	s_add_i32 s1, s19, s1
	v_cmp_gt_u32_e64 s[94:95], 16, v0
	v_sub_u32_e32 v0, v1, v3
	s_max_i32 s1, s1, 4
	v_cmp_gt_u32_e64 s[96:97], 16, v0
	v_or_b32_e32 v0, 26, v97
	s_add_i32 s1, s1, -4
	v_or_b32_e32 v1, 58, v97
	v_sub_u32_e32 v0, v0, v3
	s_min_u32 s12, s1, 56
	v_cmp_gt_u32_e64 s[4:5], 16, v0
	v_sub_u32_e32 v0, v1, v3
	s_mul_i32 s1, s14, 31
	s_mul_i32 s19, s19, 31
	v_cmp_gt_u32_e64 s[6:7], 16, v0
	v_or_b32_e32 v0, 27, v97
	s_sub_i32 s1, s1, s19
	s_mulk_i32 s0, 0x7c
	v_or_b32_e32 v1, 59, v97
	v_sub_u32_e32 v0, v0, v3
	s_sub_i32 s0, s1, s0
	v_cmp_gt_u32_e64 s[8:9], 16, v0
	v_sub_u32_e32 v0, v1, v3
	s_add_i32 s21, s0, 0x5d
	s_sub_i32 s0, s14, s15
	v_cmp_gt_u32_e64 s[10:11], 16, v0
	v_lshlrev_b32_e32 v0, 2, v2
	s_lshl_b32 s0, s0, 6
	s_add_i32 s13, s12, 8
	s_add_i32 s38, s39, 15
	s_add_i32 s39, s39, 16
	v_sub_u32_e32 v101, 0, v0
	s_add_i32 s1, s0, 0xfffffd40
	v_lshl_add_u32 v0, s14, 6, v92
	s_lshl_b32 s0, s15, 6
	v_subrev_u32_e32 v0, s0, v0
	s_add_u32 s0, s24, s18
	v_add_u32_e32 v0, 0xfffffd40, v0
	s_addc_u32 s15, s25, 0
	v_ashrrev_i32_e32 v1, 31, v0
	s_add_u32 s14, s0, s16
	v_lshlrev_b64 v[0:1], 11, v[0:1]
	s_addc_u32 s15, s15, s17
	v_mov_b32_e32 v14, v131
	v_mov_b32_e32 v15, v131
	v_lshl_add_u64 v[94:95], s[14:15], 0, v[0:1]
	v_mov_b32_e32 v0, v131
	v_mov_b32_e32 v1, v131
	v_mov_b32_e32 v2, v131
	v_mov_b32_e32 v3, v131
	v_mov_b32_e32 v4, v131
	v_mov_b32_e32 v5, v131
	v_mov_b32_e32 v6, v131
	v_mov_b32_e32 v7, v131
	v_mov_b32_e32 v8, v131
	v_mov_b32_e32 v9, v131
	v_mov_b32_e32 v10, v131
	v_mov_b32_e32 v11, v131
	v_mov_b32_e32 v12, v131
	v_mov_b32_e32 v13, v131
	v_lshlrev_b32_e32 v130, 1, v16
	v_mov_b64_e32 v[30:31], v[14:15]
	v_add_u32_e32 v100, 0x1200, v99
	s_mov_b32 s15, -1
	s_add_i32 s1, s1, 64
	s_mov_b64 s[16:17], 0x20000
	s_nop 0
	v_lshl_add_u64 v[94:95], v[94:95], 0, s[16:17]
	s_mov_b32 s32, 0
	v_mov_b32_e32 v102, 0
	v_mov_b32_e32 v96, 0xff800000
	v_mov_b64_e32 v[28:29], v[12:13]
	v_mov_b64_e32 v[26:27], v[10:11]
	v_mov_b64_e32 v[24:25], v[8:9]
	v_mov_b64_e32 v[22:23], v[6:7]
	v_mov_b64_e32 v[20:21], v[4:5]
	v_mov_b64_e32 v[18:19], v[2:3]
	v_mov_b64_e32 v[16:17], v[0:1]
	v_add_u32_e32 v32, 0x2000, v93
	s_waitcnt vmcnt(1)
	ds_write_b128 v91, v[80:83]
	s_waitcnt vmcnt(0)
	ds_write2_b64 v32, v[84:85], v[86:87] offset0:128 offset1:130
	v_mul_f32_e32 v157, 0x3fb8aa3b, v157
	ds_write_b32 v156, v157 offset:40960
	s_waitcnt lgkmcnt(0)
	s_barrier
